# sample attention: each wave of a query-group pair loads one 32-column half of the V half-tile, packs it to bf16 and shares it through a double-buffered LDS tile (16 value loads per step instead of 32,
# baseline (speedup 1.0000x reference)
; __device__ __forceinline__ void sattn_unit(const Args& a, LAS unsigned char* lds, const LAS float* bt, int db, int h, int t, int tid, int wave, int lane) {
;     ...
;     for (int it = 0; it < nf; ++it) {
;         const int key0 = __builtin_amdgcn_readfirstlane((tile0 + it) * 32);
;         bf16x8 kf[4]; bf16x8 vf[2][2];
;         SA_CVT();
;         if (it + 1 < nf) SA_LOAD(key0 + 32);
.Lks_m0:
	v_readlane_b32 s34, v251, 10
	v_mbcnt_lo_u32_b32 v249, -1, 0
	v_mbcnt_hi_u32_b32 v249, -1, v249
	v_lshlrev_b32_e32 v249, 4, v249
	s_lshl_b32 s14, s34, 11
	s_add_i32 s14, s14, 0x12800
	v_add_u32_e32 v248, s14, v249
	s_lshr_b32 s14, s34, 1
	s_lshl_b32 s14, s14, 12
	s_add_i32 s14, s14, 0x12800
	v_add_u32_e32 v249, s14, v249
	s_bitcmp1_b32 s34, 0
	s_cbranch_scc1 .Lvs_q1
	v_mov_b32_e32 v250, v134
	v_cvt_pk_bf16_f32 v88, v176, v179
	v_cvt_pk_bf16_f32 v89, v195, v204
	v_cvt_pk_bf16_f32 v90, v219, v228
	v_cvt_pk_bf16_f32 v91, v239, v242
	v_cvt_pk_bf16_f32 v92, v175, v178
	v_cvt_pk_bf16_f32 v93, v186, v202
	v_cvt_pk_bf16_f32 v94, v218, v226
	v_cvt_pk_bf16_f32 v95, v238, v241
	s_branch .Lvs_wr
.Lvs_q1:
	v_mov_b32_e32 v250, v136
	v_cvt_pk_bf16_f32 v88, v174, v177
	v_cvt_pk_bf16_f32 v89, v184, v200
	v_cvt_pk_bf16_f32 v90, v216, v224
	v_cvt_pk_bf16_f32 v91, v237, v240
	v_cvt_pk_bf16_f32 v92, v173, v180
	v_cvt_pk_bf16_f32 v93, v183, v207
	v_cvt_pk_bf16_f32 v94, v214, v231
	v_cvt_pk_bf16_f32 v95, v236, v243
.Lvs_wr:
	ds_write_b128 v248, v[88:91]
	ds_write_b128 v248, v[92:95] offset:1024
	s_mov_b32 s34, 0x4000
	s_lshl_b32 s81, s81, 15
	s_movk_i32 s32, 0x2200
.LBB0_295:
	ds_write_b128 v172, v[64:67] offset:40960
	ds_write_b128 v172, v[68:71] offset:42048
	s_waitcnt lgkmcnt(0)
	s_barrier
	ds_read_b128 v[72:75], v249
	ds_read_b128 v[76:79], v249 offset:1024
	ds_read_b128 v[80:83], v249 offset:2048
	ds_read_b128 v[84:87], v249 offset:3072
	ds_read_b128 v[108:111], v170 offset:40960
	ds_read_b128 v[104:107], v170 offset:40976
	ds_read_b128 v[100:103], v170 offset:41024
	ds_read_b128 v[96:99], v170 offset:41040
	ds_read_b128 v[44:47], v170 offset:41088
	ds_read_b128 v[40:43], v170 offset:41104
	ds_read_b128 v[36:39], v170 offset:41152
	ds_read_b128 v[32:35], v170 offset:41168
	v_add_u32_e32 v170, s32, v170
	v_add_u32_e32 v172, s32, v172
	s_sub_i32 s32, 0, s32
	v_add_u32_e32 v249, s34, v249
	v_add_u32_e32 v248, s34, v248
	s_sub_i32 s34, 0, s34
	s_add_i32 s0, s96, s35
	s_lshl_b32 vcc_lo, s0, 5
	s_add_i32 s35, s35, 1
	s_cmp_ge_u32 s35, s97
	s_cbranch_scc1 .LBB0_297
	s_add_i32 s0, s30, vcc_lo
	s_ashr_i32 s1, s0, 31
	s_lshl_b64 s[0:1], s[0:1], 12
	s_lshl_b32 s14, s5, 2
	s_or_b32 s0, s0, s14
	s_add_u32 s48, s93, s0
	s_addc_u32 s49, s89, s1
	s_add_u32 s48, s48, s81
	s_addc_u32 s49, s49, 0
	s_add_u32 s0, s42, s0
	s_addc_u32 s1, s43, s1
	v_lshl_add_u64 v[64:65], v[112:113], 2, s[48:49]
	v_lshl_add_u64 v[68:69], v[120:121], 2, s[48:49]
	global_load_dwordx4 v[64:67], v[64:65], off
	s_nop 0
	global_load_dwordx4 v[68:71], v[68:69], off
	s_nop 0
	global_load_dword v176, v250, s[0:1]
	s_add_u32 s14, s0, 0x10000
	s_addc_u32 s15, s1, 0
	global_load_dword v175, v250, s[14:15]
	s_add_u32 s48, s0, 0x1000
	s_addc_u32 s49, s1, 0
	global_load_dword v179, v250, s[48:49]
	s_add_u32 s14, s0, 0x11000
	s_addc_u32 s15, s1, 0
	global_load_dword v178, v250, s[14:15]
	s_add_u32 s48, s0, 0x2000
	s_addc_u32 s49, s1, 0
	global_load_dword v195, v250, s[48:49]
	s_add_u32 s14, s0, 0x12000
	s_addc_u32 s15, s1, 0
	global_load_dword v186, v250, s[14:15]
	s_add_u32 s48, s0, 0x3000
	s_addc_u32 s49, s1, 0
	global_load_dword v204, v250, s[48:49]
	s_add_u32 s14, s0, 0x13000
	s_addc_u32 s15, s1, 0
	global_load_dword v202, v250, s[14:15]
	s_add_u32 s48, s0, 0x8000
	s_addc_u32 s49, s1, 0
	global_load_dword v219, v250, s[48:49]
	s_add_u32 s14, s0, 0x18000
	s_addc_u32 s15, s1, 0
	global_load_dword v218, v250, s[14:15]
	s_add_u32 s48, s0, 0x9000
	s_addc_u32 s49, s1, 0
	global_load_dword v228, v250, s[48:49]
	s_add_u32 s14, s0, 0x19000
	s_addc_u32 s15, s1, 0
	global_load_dword v226, v250, s[14:15]
	s_add_u32 s48, s0, 0xa000
	s_addc_u32 s49, s1, 0
	global_load_dword v239, v250, s[48:49]
	s_add_u32 s14, s0, 0x1a000
	s_addc_u32 s15, s1, 0
	global_load_dword v238, v250, s[14:15]
	s_add_u32 s48, s0, 0xb000
	s_addc_u32 s49, s1, 0
	global_load_dword v242, v250, s[48:49]
	s_add_u32 s14, s0, 0x1b000
	s_addc_u32 s15, s1, 0
	global_load_dword v241, v250, s[14:15]

.LBB0_301:
	v_sub_f32_e32 v32, v32, v104
	v_exp_f32_e32 v32, v32
	v_sub_f32_e32 v33, v33, v104
	v_exp_f32_e32 v33, v33
	v_sub_f32_e32 v34, v34, v104
	v_exp_f32_e32 v34, v34
	v_sub_f32_e32 v35, v35, v104
	v_sub_f32_e32 v36, v36, v104
	v_sub_f32_e32 v37, v37, v104
	v_sub_f32_e32 v38, v38, v104
	v_sub_f32_e32 v39, v39, v104
	v_exp_f32_e32 v35, v35
	v_exp_f32_e32 v36, v36
	v_exp_f32_e32 v37, v37
	v_exp_f32_e32 v38, v38
	v_exp_f32_e32 v39, v39
	v_add_f32_e32 v105, 0, v32
	v_add_f32_e32 v105, v33, v105
	v_add_f32_e32 v105, v34, v105
	v_add_f32_e32 v105, v35, v105
	v_cvt_pk_bf16_f32 v32, v32, v33
	v_cvt_pk_bf16_f32 v33, v34, v35
	v_cvt_pk_bf16_f32 v34, v36, v37
	v_cvt_pk_bf16_f32 v35, v38, v39
	v_sub_f32_e32 v40, v40, v104
	v_sub_f32_e32 v41, v41, v104
	v_sub_f32_e32 v42, v42, v104
	v_sub_f32_e32 v43, v43, v104
	v_sub_f32_e32 v44, v44, v104
	v_sub_f32_e32 v45, v45, v104
	v_sub_f32_e32 v46, v46, v104
	v_sub_f32_e32 v47, v47, v104
	v_exp_f32_e32 v40, v40
	v_exp_f32_e32 v41, v41
	v_exp_f32_e32 v42, v42
	v_exp_f32_e32 v43, v43
	v_exp_f32_e32 v44, v44
	v_exp_f32_e32 v45, v45
	v_exp_f32_e32 v46, v46
	v_exp_f32_e32 v47, v47
	v_add_f32_e32 v105, v36, v105
	v_mfma_f32_32x32x16_bf16 v[0:15], v[32:35], v[72:75], v[0:15]
	v_add_f32_e32 v105, v37, v105
	v_add_f32_e32 v105, v38, v105
	v_add_f32_e32 v105, v39, v105
	v_cvt_pk_bf16_f32 v36, v40, v41
	v_cvt_pk_bf16_f32 v37, v42, v43
	v_cvt_pk_bf16_f32 v38, v44, v45
	v_cvt_pk_bf16_f32 v39, v46, v47
	v_mfma_f32_32x32x16_bf16 v[16:31], v[32:35], v[80:83], v[16:31]
	v_add_f32_e32 v105, v40, v105
	v_add_f32_e32 v105, v41, v105
	v_mfma_f32_32x32x16_bf16 v[0:15], v[36:39], v[76:79], v[0:15]
	v_add_f32_e32 v105, v42, v105
	v_add_f32_e32 v105, v43, v105
	v_add_f32_e32 v105, v44, v105
	v_add_f32_e32 v105, v45, v105
	v_add_f32_e32 v105, v46, v105
	v_add_f32_e32 v105, v47, v105
	v_add_f32_e32 v169, v105, v169
	v_mfma_f32_32x32x16_bf16 v[16:31], v[36:39], v[84:87], v[16:31]
	s_cmp_eq_u32 s97, s35
	s_cbranch_scc1 .LBB0_303
	s_waitcnt vmcnt(0)
	v_cvt_pk_bf16_f32 v88, v176, v179
	v_cvt_pk_bf16_f32 v89, v195, v204
	v_cvt_pk_bf16_f32 v90, v219, v228
	v_cvt_pk_bf16_f32 v91, v239, v242
	v_cvt_pk_bf16_f32 v92, v175, v178
	v_cvt_pk_bf16_f32 v93, v186, v202
	v_cvt_pk_bf16_f32 v94, v218, v226
	v_cvt_pk_bf16_f32 v95, v238, v241
	ds_write_b128 v248, v[88:91]
	ds_write_b128 v248, v[92:95] offset:1024
	v_mov_b32_e32 v244, v104
	s_branch .LBB0_295
